# P15-row-pass-handwritten-3-rows-in-flight
# speedup vs baseline: 1.0071x; 1.0071x over previous
.LBB0_1602:
	s_cmp_lt_i32 s72, 16
	s_cselect_b64 s[2:3], -1, 0
	s_and_b64 s[0:1], s[2:3], s[0:1]
	s_andn2_b64 vcc, exec, s[0:1]
	s_cbranch_vccnz .LBB0_1608
	s_cmpk_gt_i32 s96, 0x21ff
	s_cbranch_scc1 .LBB0_1608
	v_readlane_b32 s0, v242, 12
	v_readlane_b32 s1, v242, 13
	v_readlane_b32 s6, v242, 51
	v_readlane_b32 s7, v242, 52
	v_lshlrev_b32_e32 v252, 3, v142
	v_lshlrev_b32_e32 v253, 4, v142
	v_add_u32_e32 v254, 0x1000, v253
	v_mov_b32_e32 v255, 0x358637bd
	v_xor_b32_e32 v128, 1, v142
	v_lshlrev_b32_e32 v244, 2, v128
	v_xor_b32_e32 v128, 2, v142
	v_lshlrev_b32_e32 v245, 2, v128
	v_xor_b32_e32 v128, 4, v142
	v_lshlrev_b32_e32 v246, 2, v128
	v_xor_b32_e32 v128, 8, v142
	v_lshlrev_b32_e32 v247, 2, v128
	v_xor_b32_e32 v128, 16, v142
	v_lshlrev_b32_e32 v248, 2, v128
	v_xor_b32_e32 v128, 32, v142
	v_lshlrev_b32_e32 v249, 2, v128
	s_add_u32 s0, s0, 0x2000
	s_addc_u32 s1, s1, 0
	global_load_dwordx4 v[0:3], v253, s[0:1] offset:0
	global_load_dwordx4 v[4:7], v253, s[0:1] offset:1024
	global_load_dwordx4 v[8:11], v253, s[0:1] offset:2048
	global_load_dwordx4 v[12:15], v253, s[0:1] offset:3072
	global_load_dwordx4 v[16:19], v254, s[0:1] offset:0
	global_load_dwordx4 v[20:23], v254, s[0:1] offset:1024
	global_load_dwordx4 v[24:27], v254, s[0:1] offset:2048
	global_load_dwordx4 v[28:31], v254, s[0:1] offset:3072
	s_ashr_i32 s97, s96, 31
	s_lshl_b64 s[4:5], s[96:97], 12
	s_add_u32 s0, s6, s4
	s_addc_u32 s1, s7, s5
	s_add_u32 s2, s40, s4
	s_addc_u32 s3, s41, s5
	global_load_dwordx2 v[32:33], v252, s[0:1] offset:0
	global_load_dwordx2 v[34:35], v252, s[0:1] offset:512
	global_load_dwordx2 v[36:37], v252, s[0:1] offset:1024
	global_load_dwordx2 v[38:39], v252, s[0:1] offset:1536
	global_load_dwordx2 v[40:41], v252, s[0:1] offset:2048
	global_load_dwordx2 v[42:43], v252, s[0:1] offset:2560
	global_load_dwordx2 v[44:45], v252, s[0:1] offset:3072
	global_load_dwordx2 v[46:47], v252, s[0:1] offset:3584
	global_load_dwordx2 v[48:49], v252, s[2:3] offset:0
	global_load_dwordx2 v[50:51], v252, s[2:3] offset:512
	global_load_dwordx2 v[52:53], v252, s[2:3] offset:1024
	global_load_dwordx2 v[54:55], v252, s[2:3] offset:1536
	global_load_dwordx2 v[56:57], v252, s[2:3] offset:2048
	global_load_dwordx2 v[58:59], v252, s[2:3] offset:2560
	global_load_dwordx2 v[60:61], v252, s[2:3] offset:3072
	global_load_dwordx2 v[62:63], v252, s[2:3] offset:3584
	s_add_u32 s0, s0, 0x800000
	s_addc_u32 s1, s1, 0
	s_add_u32 s2, s2, 0x800000
	s_addc_u32 s3, s3, 0
	global_load_dwordx2 v[64:65], v252, s[0:1] offset:0
	global_load_dwordx2 v[66:67], v252, s[0:1] offset:512
	global_load_dwordx2 v[68:69], v252, s[0:1] offset:1024
	global_load_dwordx2 v[70:71], v252, s[0:1] offset:1536
	global_load_dwordx2 v[72:73], v252, s[0:1] offset:2048
	global_load_dwordx2 v[74:75], v252, s[0:1] offset:2560
	global_load_dwordx2 v[76:77], v252, s[0:1] offset:3072
	global_load_dwordx2 v[78:79], v252, s[0:1] offset:3584
	global_load_dwordx2 v[80:81], v252, s[2:3] offset:0
	global_load_dwordx2 v[82:83], v252, s[2:3] offset:512
	global_load_dwordx2 v[84:85], v252, s[2:3] offset:1024
	global_load_dwordx2 v[86:87], v252, s[2:3] offset:1536
	global_load_dwordx2 v[88:89], v252, s[2:3] offset:2048
	global_load_dwordx2 v[90:91], v252, s[2:3] offset:2560
	global_load_dwordx2 v[92:93], v252, s[2:3] offset:3072
	global_load_dwordx2 v[94:95], v252, s[2:3] offset:3584
	s_add_u32 s0, s0, 0x800000
	s_addc_u32 s1, s1, 0
	s_add_u32 s2, s2, 0x800000
	s_addc_u32 s3, s3, 0
	global_load_dwordx2 v[96:97], v252, s[0:1] offset:0
	global_load_dwordx2 v[98:99], v252, s[0:1] offset:512
	global_load_dwordx2 v[100:101], v252, s[0:1] offset:1024
	global_load_dwordx2 v[102:103], v252, s[0:1] offset:1536
	global_load_dwordx2 v[104:105], v252, s[0:1] offset:2048
	global_load_dwordx2 v[106:107], v252, s[0:1] offset:2560
	global_load_dwordx2 v[108:109], v252, s[0:1] offset:3072
	global_load_dwordx2 v[110:111], v252, s[0:1] offset:3584
	global_load_dwordx2 v[112:113], v252, s[2:3] offset:0
	global_load_dwordx2 v[114:115], v252, s[2:3] offset:512
	global_load_dwordx2 v[116:117], v252, s[2:3] offset:1024
	global_load_dwordx2 v[118:119], v252, s[2:3] offset:1536
	global_load_dwordx2 v[120:121], v252, s[2:3] offset:2048
	global_load_dwordx2 v[122:123], v252, s[2:3] offset:2560
	global_load_dwordx2 v[124:125], v252, s[2:3] offset:3072
	global_load_dwordx2 v[126:127], v252, s[2:3] offset:3584
	s_add_u32 s0, s0, 0x800000
	s_addc_u32 s1, s1, 0
	s_add_u32 s2, s2, 0x800000
	s_addc_u32 s3, s3, 0
	s_lshl_b64 s[4:5], s[96:97], 13
	s_add_u32 s4, s68, s4
	s_addc_u32 s5, s69, s5
	v_mov_b32_e32 v250, v253
	v_mov_b32_e32 v251, 0
	v_lshl_add_u64 v[250:251], s[4:5], 0, v[250:251]
	s_mov_b64 s[12:13], 0x1000000
	s_mov_b64 s[14:15], 0x1000
	s_mov_b32 s10, 0x800000
	s_waitcnt vmcnt(32)
	v_lshlrev_b32_e32 v208, 16, v48
	v_and_b32_e32 v209, 0xffff0000, v48
	v_lshlrev_b32_e32 v210, 16, v49
	v_and_b32_e32 v211, 0xffff0000, v49
	v_lshlrev_b32_e32 v212, 16, v50
	v_and_b32_e32 v213, 0xffff0000, v50
	v_lshlrev_b32_e32 v214, 16, v51
	v_and_b32_e32 v215, 0xffff0000, v51
	v_lshlrev_b32_e32 v216, 16, v52
	v_and_b32_e32 v217, 0xffff0000, v52
	v_lshlrev_b32_e32 v218, 16, v53
	v_and_b32_e32 v219, 0xffff0000, v53
	v_lshlrev_b32_e32 v220, 16, v54
	v_and_b32_e32 v221, 0xffff0000, v54
	v_lshlrev_b32_e32 v222, 16, v55
	v_and_b32_e32 v223, 0xffff0000, v55
	v_lshlrev_b32_e32 v224, 16, v56
	v_and_b32_e32 v225, 0xffff0000, v56
	v_lshlrev_b32_e32 v226, 16, v57
	v_and_b32_e32 v227, 0xffff0000, v57
	v_lshlrev_b32_e32 v228, 16, v58
	v_and_b32_e32 v229, 0xffff0000, v58
	v_lshlrev_b32_e32 v230, 16, v59
	v_and_b32_e32 v231, 0xffff0000, v59
	v_lshlrev_b32_e32 v232, 16, v60
	v_and_b32_e32 v233, 0xffff0000, v60
	v_lshlrev_b32_e32 v234, 16, v61
	v_and_b32_e32 v235, 0xffff0000, v61
	v_lshlrev_b32_e32 v236, 16, v62
	v_and_b32_e32 v237, 0xffff0000, v62
	v_lshlrev_b32_e32 v238, 16, v63
	v_and_b32_e32 v239, 0xffff0000, v63
	v_mul_f32_e32 v128, v208, v208
	v_fmac_f32_e32 v128, v209, v209
	v_mul_f32_e32 v129, v210, v210
	v_fmac_f32_e32 v129, v211, v211
	v_add_f32_e32 v128, v128, v129
	v_mul_f32_e32 v129, v212, v212
	v_fmac_f32_e32 v129, v213, v213
	v_mul_f32_e32 v132, v214, v214
	v_fmac_f32_e32 v132, v215, v215
	v_add_f32_e32 v129, v129, v132
	v_add_f32_e32 v128, v128, v129
	v_mul_f32_e32 v129, v216, v216
	v_fmac_f32_e32 v129, v217, v217
	v_mul_f32_e32 v132, v218, v218
	v_fmac_f32_e32 v132, v219, v219
	v_add_f32_e32 v129, v129, v132
	v_add_f32_e32 v128, v128, v129
	v_mul_f32_e32 v129, v220, v220
	v_fmac_f32_e32 v129, v221, v221
	v_mul_f32_e32 v132, v222, v222
	v_fmac_f32_e32 v132, v223, v223
	v_add_f32_e32 v129, v129, v132
	v_add_f32_e32 v128, v128, v129
	v_mul_f32_e32 v129, v224, v224
	v_fmac_f32_e32 v129, v225, v225
	v_mul_f32_e32 v132, v226, v226
	v_fmac_f32_e32 v132, v227, v227
	v_add_f32_e32 v129, v129, v132
	v_add_f32_e32 v128, v128, v129
	v_mul_f32_e32 v129, v228, v228
	v_fmac_f32_e32 v129, v229, v229
	v_mul_f32_e32 v132, v230, v230
	v_fmac_f32_e32 v132, v231, v231
	v_add_f32_e32 v129, v129, v132
	v_add_f32_e32 v128, v128, v129
	v_mul_f32_e32 v129, v232, v232
	v_fmac_f32_e32 v129, v233, v233
	v_mul_f32_e32 v132, v234, v234
	v_fmac_f32_e32 v132, v235, v235
	v_add_f32_e32 v129, v129, v132
	v_add_f32_e32 v128, v128, v129
	v_mul_f32_e32 v129, v236, v236
	v_fmac_f32_e32 v129, v237, v237
	v_mul_f32_e32 v132, v238, v238
	v_fmac_f32_e32 v132, v239, v239
	v_add_f32_e32 v129, v129, v132
	v_add_f32_e32 v128, v128, v129
	ds_bpermute_b32 v129, v244, v128
	s_waitcnt lgkmcnt(0)
	v_add_f32_e32 v128, v128, v129
	ds_bpermute_b32 v129, v245, v128
	s_waitcnt lgkmcnt(0)
	v_add_f32_e32 v128, v128, v129
	ds_bpermute_b32 v129, v246, v128
	s_waitcnt lgkmcnt(0)
	v_add_f32_e32 v128, v128, v129
	ds_bpermute_b32 v129, v247, v128
	s_waitcnt lgkmcnt(0)
	v_add_f32_e32 v128, v128, v129
	ds_bpermute_b32 v129, v248, v128
	s_waitcnt lgkmcnt(0)
	v_add_f32_e32 v128, v128, v129
	ds_bpermute_b32 v129, v249, v128
	s_waitcnt lgkmcnt(0)
	v_add_f32_e32 v128, v128, v129
	v_fmamk_f32 v128, v128, 0x3a000000, v255
	v_mul_f32_e32 v129, 0x4b800000, v128
	v_cmp_gt_f32_e32 vcc, s10, v128
	s_nop 1
	v_cndmask_b32_e32 v128, v128, v129, vcc
	v_rsq_f32_e32 v128, v128
	s_nop 0
	v_mul_f32_e32 v129, 0x45800000, v128
	v_cndmask_b32_e32 v130, v128, v129, vcc
	v_lshl_add_u64 v[140:141], v[250:251], 0, s[14:15]
	v_lshlrev_b32_e32 v136, 16, v32
	v_and_b32_e32 v137, 0xffff0000, v32
	v_lshlrev_b32_e32 v138, 16, v33
	v_and_b32_e32 v139, 0xffff0000, v33
	v_pk_mul_f32 v[208:209], v[130:131], v[208:209] op_sel_hi:[0,1]
	v_pk_fma_f32 v[208:209], v[0:1], v[208:209], v[136:137]
	v_pk_mul_f32 v[210:211], v[130:131], v[210:211] op_sel_hi:[0,1]
	v_pk_fma_f32 v[210:211], v[2:3], v[210:211], v[138:139]
	global_store_dwordx4 v[250:251], v[208:211], off offset:0
	v_lshlrev_b32_e32 v136, 16, v34
	v_and_b32_e32 v137, 0xffff0000, v34
	v_lshlrev_b32_e32 v138, 16, v35
	v_and_b32_e32 v139, 0xffff0000, v35
	v_pk_mul_f32 v[212:213], v[130:131], v[212:213] op_sel_hi:[0,1]
	v_pk_fma_f32 v[212:213], v[4:5], v[212:213], v[136:137]
	v_pk_mul_f32 v[214:215], v[130:131], v[214:215] op_sel_hi:[0,1]
	v_pk_fma_f32 v[214:215], v[6:7], v[214:215], v[138:139]
	global_store_dwordx4 v[250:251], v[212:215], off offset:1024
	v_lshlrev_b32_e32 v136, 16, v36
	v_and_b32_e32 v137, 0xffff0000, v36
	v_lshlrev_b32_e32 v138, 16, v37
	v_and_b32_e32 v139, 0xffff0000, v37
	v_pk_mul_f32 v[216:217], v[130:131], v[216:217] op_sel_hi:[0,1]
	v_pk_fma_f32 v[216:217], v[8:9], v[216:217], v[136:137]
	v_pk_mul_f32 v[218:219], v[130:131], v[218:219] op_sel_hi:[0,1]
	v_pk_fma_f32 v[218:219], v[10:11], v[218:219], v[138:139]
	global_store_dwordx4 v[250:251], v[216:219], off offset:2048
	v_lshlrev_b32_e32 v136, 16, v38
	v_and_b32_e32 v137, 0xffff0000, v38
	v_lshlrev_b32_e32 v138, 16, v39
	v_and_b32_e32 v139, 0xffff0000, v39
	v_pk_mul_f32 v[220:221], v[130:131], v[220:221] op_sel_hi:[0,1]
	v_pk_fma_f32 v[220:221], v[12:13], v[220:221], v[136:137]
	v_pk_mul_f32 v[222:223], v[130:131], v[222:223] op_sel_hi:[0,1]
	v_pk_fma_f32 v[222:223], v[14:15], v[222:223], v[138:139]
	global_store_dwordx4 v[250:251], v[220:223], off offset:3072
	v_lshlrev_b32_e32 v136, 16, v40
	v_and_b32_e32 v137, 0xffff0000, v40
	v_lshlrev_b32_e32 v138, 16, v41
	v_and_b32_e32 v139, 0xffff0000, v41
	v_pk_mul_f32 v[224:225], v[130:131], v[224:225] op_sel_hi:[0,1]
	v_pk_fma_f32 v[224:225], v[16:17], v[224:225], v[136:137]
	v_pk_mul_f32 v[226:227], v[130:131], v[226:227] op_sel_hi:[0,1]
	v_pk_fma_f32 v[226:227], v[18:19], v[226:227], v[138:139]
	global_store_dwordx4 v[140:141], v[224:227], off offset:0
	v_lshlrev_b32_e32 v136, 16, v42
	v_and_b32_e32 v137, 0xffff0000, v42
	v_lshlrev_b32_e32 v138, 16, v43
	v_and_b32_e32 v139, 0xffff0000, v43
	v_pk_mul_f32 v[228:229], v[130:131], v[228:229] op_sel_hi:[0,1]
	v_pk_fma_f32 v[228:229], v[20:21], v[228:229], v[136:137]
	v_pk_mul_f32 v[230:231], v[130:131], v[230:231] op_sel_hi:[0,1]
	v_pk_fma_f32 v[230:231], v[22:23], v[230:231], v[138:139]
	global_store_dwordx4 v[140:141], v[228:231], off offset:1024
	v_lshlrev_b32_e32 v136, 16, v44
	v_and_b32_e32 v137, 0xffff0000, v44
	v_lshlrev_b32_e32 v138, 16, v45
	v_and_b32_e32 v139, 0xffff0000, v45
	v_pk_mul_f32 v[232:233], v[130:131], v[232:233] op_sel_hi:[0,1]
	v_pk_fma_f32 v[232:233], v[24:25], v[232:233], v[136:137]
	v_pk_mul_f32 v[234:235], v[130:131], v[234:235] op_sel_hi:[0,1]
	v_pk_fma_f32 v[234:235], v[26:27], v[234:235], v[138:139]
	global_store_dwordx4 v[140:141], v[232:235], off offset:2048
	v_lshlrev_b32_e32 v136, 16, v46
	v_and_b32_e32 v137, 0xffff0000, v46
	v_lshlrev_b32_e32 v138, 16, v47
	v_and_b32_e32 v139, 0xffff0000, v47
	v_pk_mul_f32 v[236:237], v[130:131], v[236:237] op_sel_hi:[0,1]
	v_pk_fma_f32 v[236:237], v[28:29], v[236:237], v[136:137]
	v_pk_mul_f32 v[238:239], v[130:131], v[238:239] op_sel_hi:[0,1]
	v_pk_fma_f32 v[238:239], v[30:31], v[238:239], v[138:139]
	global_store_dwordx4 v[140:141], v[236:239], off offset:3072
	v_lshl_add_u64 v[250:251], v[250:251], 0, s[12:13]
	global_load_dwordx2 v[144:145], v252, s[0:1] offset:0
	global_load_dwordx2 v[146:147], v252, s[0:1] offset:512
	global_load_dwordx2 v[148:149], v252, s[0:1] offset:1024
	global_load_dwordx2 v[150:151], v252, s[0:1] offset:1536
	global_load_dwordx2 v[152:153], v252, s[0:1] offset:2048
	global_load_dwordx2 v[154:155], v252, s[0:1] offset:2560
	global_load_dwordx2 v[156:157], v252, s[0:1] offset:3072
	global_load_dwordx2 v[158:159], v252, s[0:1] offset:3584
	global_load_dwordx2 v[160:161], v252, s[2:3] offset:0
	global_load_dwordx2 v[162:163], v252, s[2:3] offset:512
	global_load_dwordx2 v[164:165], v252, s[2:3] offset:1024
	global_load_dwordx2 v[166:167], v252, s[2:3] offset:1536
	global_load_dwordx2 v[168:169], v252, s[2:3] offset:2048
	global_load_dwordx2 v[170:171], v252, s[2:3] offset:2560
	global_load_dwordx2 v[172:173], v252, s[2:3] offset:3072
	global_load_dwordx2 v[174:175], v252, s[2:3] offset:3584
	s_add_u32 s0, s0, 0x800000
	s_addc_u32 s1, s1, 0
	s_add_u32 s2, s2, 0x800000
	s_addc_u32 s3, s3, 0
	s_waitcnt vmcnt(40)
	v_lshlrev_b32_e32 v208, 16, v80
	v_and_b32_e32 v209, 0xffff0000, v80
	v_lshlrev_b32_e32 v210, 16, v81
	v_and_b32_e32 v211, 0xffff0000, v81
	v_lshlrev_b32_e32 v212, 16, v82
	v_and_b32_e32 v213, 0xffff0000, v82
	v_lshlrev_b32_e32 v214, 16, v83
	v_and_b32_e32 v215, 0xffff0000, v83
	v_lshlrev_b32_e32 v216, 16, v84
	v_and_b32_e32 v217, 0xffff0000, v84
	v_lshlrev_b32_e32 v218, 16, v85
	v_and_b32_e32 v219, 0xffff0000, v85
	v_lshlrev_b32_e32 v220, 16, v86
	v_and_b32_e32 v221, 0xffff0000, v86
	v_lshlrev_b32_e32 v222, 16, v87
	v_and_b32_e32 v223, 0xffff0000, v87
	v_lshlrev_b32_e32 v224, 16, v88
	v_and_b32_e32 v225, 0xffff0000, v88
	v_lshlrev_b32_e32 v226, 16, v89
	v_and_b32_e32 v227, 0xffff0000, v89
	v_lshlrev_b32_e32 v228, 16, v90
	v_and_b32_e32 v229, 0xffff0000, v90
	v_lshlrev_b32_e32 v230, 16, v91
	v_and_b32_e32 v231, 0xffff0000, v91
	v_lshlrev_b32_e32 v232, 16, v92
	v_and_b32_e32 v233, 0xffff0000, v92
	v_lshlrev_b32_e32 v234, 16, v93
	v_and_b32_e32 v235, 0xffff0000, v93
	v_lshlrev_b32_e32 v236, 16, v94
	v_and_b32_e32 v237, 0xffff0000, v94
	v_lshlrev_b32_e32 v238, 16, v95
	v_and_b32_e32 v239, 0xffff0000, v95
	v_mul_f32_e32 v128, v208, v208
	v_fmac_f32_e32 v128, v209, v209
	v_mul_f32_e32 v129, v210, v210
	v_fmac_f32_e32 v129, v211, v211
	v_add_f32_e32 v128, v128, v129
	v_mul_f32_e32 v129, v212, v212
	v_fmac_f32_e32 v129, v213, v213
	v_mul_f32_e32 v132, v214, v214
	v_fmac_f32_e32 v132, v215, v215
	v_add_f32_e32 v129, v129, v132
	v_add_f32_e32 v128, v128, v129
	v_mul_f32_e32 v129, v216, v216
	v_fmac_f32_e32 v129, v217, v217
	v_mul_f32_e32 v132, v218, v218
	v_fmac_f32_e32 v132, v219, v219
	v_add_f32_e32 v129, v129, v132
	v_add_f32_e32 v128, v128, v129
	v_mul_f32_e32 v129, v220, v220
	v_fmac_f32_e32 v129, v221, v221
	v_mul_f32_e32 v132, v222, v222
	v_fmac_f32_e32 v132, v223, v223
	v_add_f32_e32 v129, v129, v132
	v_add_f32_e32 v128, v128, v129
	v_mul_f32_e32 v129, v224, v224
	v_fmac_f32_e32 v129, v225, v225
	v_mul_f32_e32 v132, v226, v226
	v_fmac_f32_e32 v132, v227, v227
	v_add_f32_e32 v129, v129, v132
	v_add_f32_e32 v128, v128, v129
	v_mul_f32_e32 v129, v228, v228
	v_fmac_f32_e32 v129, v229, v229
	v_mul_f32_e32 v132, v230, v230
	v_fmac_f32_e32 v132, v231, v231
	v_add_f32_e32 v129, v129, v132
	v_add_f32_e32 v128, v128, v129
	v_mul_f32_e32 v129, v232, v232
	v_fmac_f32_e32 v129, v233, v233
	v_mul_f32_e32 v132, v234, v234
	v_fmac_f32_e32 v132, v235, v235
	v_add_f32_e32 v129, v129, v132
	v_add_f32_e32 v128, v128, v129
	v_mul_f32_e32 v129, v236, v236
	v_fmac_f32_e32 v129, v237, v237
	v_mul_f32_e32 v132, v238, v238
	v_fmac_f32_e32 v132, v239, v239
	v_add_f32_e32 v129, v129, v132
	v_add_f32_e32 v128, v128, v129
	ds_bpermute_b32 v129, v244, v128
	s_waitcnt lgkmcnt(0)
	v_add_f32_e32 v128, v128, v129
	ds_bpermute_b32 v129, v245, v128
	s_waitcnt lgkmcnt(0)
	v_add_f32_e32 v128, v128, v129
	ds_bpermute_b32 v129, v246, v128
	s_waitcnt lgkmcnt(0)
	v_add_f32_e32 v128, v128, v129
	ds_bpermute_b32 v129, v247, v128
	s_waitcnt lgkmcnt(0)
	v_add_f32_e32 v128, v128, v129
	ds_bpermute_b32 v129, v248, v128
	s_waitcnt lgkmcnt(0)
	v_add_f32_e32 v128, v128, v129
	ds_bpermute_b32 v129, v249, v128
	s_waitcnt lgkmcnt(0)
	v_add_f32_e32 v128, v128, v129
	v_fmamk_f32 v128, v128, 0x3a000000, v255
	v_mul_f32_e32 v129, 0x4b800000, v128
	v_cmp_gt_f32_e32 vcc, s10, v128
	s_nop 1
	v_cndmask_b32_e32 v128, v128, v129, vcc
	v_rsq_f32_e32 v128, v128
	s_nop 0
	v_mul_f32_e32 v129, 0x45800000, v128
	v_cndmask_b32_e32 v130, v128, v129, vcc
	v_lshl_add_u64 v[140:141], v[250:251], 0, s[14:15]
	v_lshlrev_b32_e32 v136, 16, v64
	v_and_b32_e32 v137, 0xffff0000, v64
	v_lshlrev_b32_e32 v138, 16, v65
	v_and_b32_e32 v139, 0xffff0000, v65
	v_pk_mul_f32 v[208:209], v[130:131], v[208:209] op_sel_hi:[0,1]
	v_pk_fma_f32 v[208:209], v[0:1], v[208:209], v[136:137]
	v_pk_mul_f32 v[210:211], v[130:131], v[210:211] op_sel_hi:[0,1]
	v_pk_fma_f32 v[210:211], v[2:3], v[210:211], v[138:139]
	global_store_dwordx4 v[250:251], v[208:211], off offset:0
	v_lshlrev_b32_e32 v136, 16, v66
	v_and_b32_e32 v137, 0xffff0000, v66
	v_lshlrev_b32_e32 v138, 16, v67
	v_and_b32_e32 v139, 0xffff0000, v67
	v_pk_mul_f32 v[212:213], v[130:131], v[212:213] op_sel_hi:[0,1]
	v_pk_fma_f32 v[212:213], v[4:5], v[212:213], v[136:137]
	v_pk_mul_f32 v[214:215], v[130:131], v[214:215] op_sel_hi:[0,1]
	v_pk_fma_f32 v[214:215], v[6:7], v[214:215], v[138:139]
	global_store_dwordx4 v[250:251], v[212:215], off offset:1024
	v_lshlrev_b32_e32 v136, 16, v68
	v_and_b32_e32 v137, 0xffff0000, v68
	v_lshlrev_b32_e32 v138, 16, v69
	v_and_b32_e32 v139, 0xffff0000, v69
	v_pk_mul_f32 v[216:217], v[130:131], v[216:217] op_sel_hi:[0,1]
	v_pk_fma_f32 v[216:217], v[8:9], v[216:217], v[136:137]
	v_pk_mul_f32 v[218:219], v[130:131], v[218:219] op_sel_hi:[0,1]
	v_pk_fma_f32 v[218:219], v[10:11], v[218:219], v[138:139]
	global_store_dwordx4 v[250:251], v[216:219], off offset:2048
	v_lshlrev_b32_e32 v136, 16, v70
	v_and_b32_e32 v137, 0xffff0000, v70
	v_lshlrev_b32_e32 v138, 16, v71
	v_and_b32_e32 v139, 0xffff0000, v71
	v_pk_mul_f32 v[220:221], v[130:131], v[220:221] op_sel_hi:[0,1]
	v_pk_fma_f32 v[220:221], v[12:13], v[220:221], v[136:137]
	v_pk_mul_f32 v[222:223], v[130:131], v[222:223] op_sel_hi:[0,1]
	v_pk_fma_f32 v[222:223], v[14:15], v[222:223], v[138:139]
	global_store_dwordx4 v[250:251], v[220:223], off offset:3072
	v_lshlrev_b32_e32 v136, 16, v72
	v_and_b32_e32 v137, 0xffff0000, v72
	v_lshlrev_b32_e32 v138, 16, v73
	v_and_b32_e32 v139, 0xffff0000, v73
	v_pk_mul_f32 v[224:225], v[130:131], v[224:225] op_sel_hi:[0,1]
	v_pk_fma_f32 v[224:225], v[16:17], v[224:225], v[136:137]
	v_pk_mul_f32 v[226:227], v[130:131], v[226:227] op_sel_hi:[0,1]
	v_pk_fma_f32 v[226:227], v[18:19], v[226:227], v[138:139]
	global_store_dwordx4 v[140:141], v[224:227], off offset:0
	v_lshlrev_b32_e32 v136, 16, v74
	v_and_b32_e32 v137, 0xffff0000, v74
	v_lshlrev_b32_e32 v138, 16, v75
	v_and_b32_e32 v139, 0xffff0000, v75
	v_pk_mul_f32 v[228:229], v[130:131], v[228:229] op_sel_hi:[0,1]
	v_pk_fma_f32 v[228:229], v[20:21], v[228:229], v[136:137]
	v_pk_mul_f32 v[230:231], v[130:131], v[230:231] op_sel_hi:[0,1]
	v_pk_fma_f32 v[230:231], v[22:23], v[230:231], v[138:139]
	global_store_dwordx4 v[140:141], v[228:231], off offset:1024
	v_lshlrev_b32_e32 v136, 16, v76
	v_and_b32_e32 v137, 0xffff0000, v76
	v_lshlrev_b32_e32 v138, 16, v77
	v_and_b32_e32 v139, 0xffff0000, v77
	v_pk_mul_f32 v[232:233], v[130:131], v[232:233] op_sel_hi:[0,1]
	v_pk_fma_f32 v[232:233], v[24:25], v[232:233], v[136:137]
	v_pk_mul_f32 v[234:235], v[130:131], v[234:235] op_sel_hi:[0,1]
	v_pk_fma_f32 v[234:235], v[26:27], v[234:235], v[138:139]
	global_store_dwordx4 v[140:141], v[232:235], off offset:2048
	v_lshlrev_b32_e32 v136, 16, v78
	v_and_b32_e32 v137, 0xffff0000, v78
	v_lshlrev_b32_e32 v138, 16, v79
	v_and_b32_e32 v139, 0xffff0000, v79
	v_pk_mul_f32 v[236:237], v[130:131], v[236:237] op_sel_hi:[0,1]
	v_pk_fma_f32 v[236:237], v[28:29], v[236:237], v[136:137]
	v_pk_mul_f32 v[238:239], v[130:131], v[238:239] op_sel_hi:[0,1]
	v_pk_fma_f32 v[238:239], v[30:31], v[238:239], v[138:139]
	global_store_dwordx4 v[140:141], v[236:239], off offset:3072
	v_lshl_add_u64 v[250:251], v[250:251], 0, s[12:13]
	s_waitcnt vmcnt(32)
	s_cmpk_gt_i32 s96, 0x1ff
	s_cbranch_scc1 .Lp15_no5a
	global_load_dwordx2 v[176:177], v252, s[0:1] offset:0
	global_load_dwordx2 v[178:179], v252, s[0:1] offset:512
	global_load_dwordx2 v[180:181], v252, s[0:1] offset:1024
	global_load_dwordx2 v[182:183], v252, s[0:1] offset:1536
	global_load_dwordx2 v[184:185], v252, s[0:1] offset:2048
	global_load_dwordx2 v[186:187], v252, s[0:1] offset:2560
	global_load_dwordx2 v[188:189], v252, s[0:1] offset:3072
	global_load_dwordx2 v[190:191], v252, s[0:1] offset:3584
	global_load_dwordx2 v[192:193], v252, s[2:3] offset:0
	global_load_dwordx2 v[194:195], v252, s[2:3] offset:512
	global_load_dwordx2 v[196:197], v252, s[2:3] offset:1024
	global_load_dwordx2 v[198:199], v252, s[2:3] offset:1536
	global_load_dwordx2 v[200:201], v252, s[2:3] offset:2048
	global_load_dwordx2 v[202:203], v252, s[2:3] offset:2560
	global_load_dwordx2 v[204:205], v252, s[2:3] offset:3072
	global_load_dwordx2 v[206:207], v252, s[2:3] offset:3584
	s_add_u32 s0, s0, 0x800000
	s_addc_u32 s1, s1, 0
	s_add_u32 s2, s2, 0x800000
	s_addc_u32 s3, s3, 0
.Lp15_no5a:
	v_lshlrev_b32_e32 v208, 16, v112
	v_and_b32_e32 v209, 0xffff0000, v112
	v_lshlrev_b32_e32 v210, 16, v113
	v_and_b32_e32 v211, 0xffff0000, v113
	v_lshlrev_b32_e32 v212, 16, v114
	v_and_b32_e32 v213, 0xffff0000, v114
	v_lshlrev_b32_e32 v214, 16, v115
	v_and_b32_e32 v215, 0xffff0000, v115
	v_lshlrev_b32_e32 v216, 16, v116
	v_and_b32_e32 v217, 0xffff0000, v116
	v_lshlrev_b32_e32 v218, 16, v117
	v_and_b32_e32 v219, 0xffff0000, v117
	v_lshlrev_b32_e32 v220, 16, v118
	v_and_b32_e32 v221, 0xffff0000, v118
	v_lshlrev_b32_e32 v222, 16, v119
	v_and_b32_e32 v223, 0xffff0000, v119
	v_lshlrev_b32_e32 v224, 16, v120
	v_and_b32_e32 v225, 0xffff0000, v120
	v_lshlrev_b32_e32 v226, 16, v121
	v_and_b32_e32 v227, 0xffff0000, v121
	v_lshlrev_b32_e32 v228, 16, v122
	v_and_b32_e32 v229, 0xffff0000, v122
	v_lshlrev_b32_e32 v230, 16, v123
	v_and_b32_e32 v231, 0xffff0000, v123
	v_lshlrev_b32_e32 v232, 16, v124
	v_and_b32_e32 v233, 0xffff0000, v124
	v_lshlrev_b32_e32 v234, 16, v125
	v_and_b32_e32 v235, 0xffff0000, v125
	v_lshlrev_b32_e32 v236, 16, v126
	v_and_b32_e32 v237, 0xffff0000, v126
	v_lshlrev_b32_e32 v238, 16, v127
	v_and_b32_e32 v239, 0xffff0000, v127
	v_mul_f32_e32 v128, v208, v208
	v_fmac_f32_e32 v128, v209, v209
	v_mul_f32_e32 v129, v210, v210
	v_fmac_f32_e32 v129, v211, v211
	v_add_f32_e32 v128, v128, v129
	v_mul_f32_e32 v129, v212, v212
	v_fmac_f32_e32 v129, v213, v213
	v_mul_f32_e32 v132, v214, v214
	v_fmac_f32_e32 v132, v215, v215
	v_add_f32_e32 v129, v129, v132
	v_add_f32_e32 v128, v128, v129
	v_mul_f32_e32 v129, v216, v216
	v_fmac_f32_e32 v129, v217, v217
	v_mul_f32_e32 v132, v218, v218
	v_fmac_f32_e32 v132, v219, v219
	v_add_f32_e32 v129, v129, v132
	v_add_f32_e32 v128, v128, v129
	v_mul_f32_e32 v129, v220, v220
	v_fmac_f32_e32 v129, v221, v221
	v_mul_f32_e32 v132, v222, v222
	v_fmac_f32_e32 v132, v223, v223
	v_add_f32_e32 v129, v129, v132
	v_add_f32_e32 v128, v128, v129
	v_mul_f32_e32 v129, v224, v224
	v_fmac_f32_e32 v129, v225, v225
	v_mul_f32_e32 v132, v226, v226
	v_fmac_f32_e32 v132, v227, v227
	v_add_f32_e32 v129, v129, v132
	v_add_f32_e32 v128, v128, v129
	v_mul_f32_e32 v129, v228, v228
	v_fmac_f32_e32 v129, v229, v229
	v_mul_f32_e32 v132, v230, v230
	v_fmac_f32_e32 v132, v231, v231
	v_add_f32_e32 v129, v129, v132
	v_add_f32_e32 v128, v128, v129
	v_mul_f32_e32 v129, v232, v232
	v_fmac_f32_e32 v129, v233, v233
	v_mul_f32_e32 v132, v234, v234
	v_fmac_f32_e32 v132, v235, v235
	v_add_f32_e32 v129, v129, v132
	v_add_f32_e32 v128, v128, v129
	v_mul_f32_e32 v129, v236, v236
	v_fmac_f32_e32 v129, v237, v237
	v_mul_f32_e32 v132, v238, v238
	v_fmac_f32_e32 v132, v239, v239
	v_add_f32_e32 v129, v129, v132
	v_add_f32_e32 v128, v128, v129
	ds_bpermute_b32 v129, v244, v128
	s_waitcnt lgkmcnt(0)
	v_add_f32_e32 v128, v128, v129
	ds_bpermute_b32 v129, v245, v128
	s_waitcnt lgkmcnt(0)
	v_add_f32_e32 v128, v128, v129
	ds_bpermute_b32 v129, v246, v128
	s_waitcnt lgkmcnt(0)
	v_add_f32_e32 v128, v128, v129
	ds_bpermute_b32 v129, v247, v128
	s_waitcnt lgkmcnt(0)
	v_add_f32_e32 v128, v128, v129
	ds_bpermute_b32 v129, v248, v128
	s_waitcnt lgkmcnt(0)
	v_add_f32_e32 v128, v128, v129
	ds_bpermute_b32 v129, v249, v128
	s_waitcnt lgkmcnt(0)
	v_add_f32_e32 v128, v128, v129
	v_fmamk_f32 v128, v128, 0x3a000000, v255
	v_mul_f32_e32 v129, 0x4b800000, v128
	v_cmp_gt_f32_e32 vcc, s10, v128
	s_nop 1
	v_cndmask_b32_e32 v128, v128, v129, vcc
	v_rsq_f32_e32 v128, v128
	s_nop 0
	v_mul_f32_e32 v129, 0x45800000, v128
	v_cndmask_b32_e32 v130, v128, v129, vcc
	v_lshl_add_u64 v[140:141], v[250:251], 0, s[14:15]
	v_lshlrev_b32_e32 v136, 16, v96
	v_and_b32_e32 v137, 0xffff0000, v96
	v_lshlrev_b32_e32 v138, 16, v97
	v_and_b32_e32 v139, 0xffff0000, v97
	v_pk_mul_f32 v[208:209], v[130:131], v[208:209] op_sel_hi:[0,1]
	v_pk_fma_f32 v[208:209], v[0:1], v[208:209], v[136:137]
	v_pk_mul_f32 v[210:211], v[130:131], v[210:211] op_sel_hi:[0,1]
	v_pk_fma_f32 v[210:211], v[2:3], v[210:211], v[138:139]
	global_store_dwordx4 v[250:251], v[208:211], off offset:0
	v_lshlrev_b32_e32 v136, 16, v98
	v_and_b32_e32 v137, 0xffff0000, v98
	v_lshlrev_b32_e32 v138, 16, v99
	v_and_b32_e32 v139, 0xffff0000, v99
	v_pk_mul_f32 v[212:213], v[130:131], v[212:213] op_sel_hi:[0,1]
	v_pk_fma_f32 v[212:213], v[4:5], v[212:213], v[136:137]
	v_pk_mul_f32 v[214:215], v[130:131], v[214:215] op_sel_hi:[0,1]
	v_pk_fma_f32 v[214:215], v[6:7], v[214:215], v[138:139]
	global_store_dwordx4 v[250:251], v[212:215], off offset:1024
	v_lshlrev_b32_e32 v136, 16, v100
	v_and_b32_e32 v137, 0xffff0000, v100
	v_lshlrev_b32_e32 v138, 16, v101
	v_and_b32_e32 v139, 0xffff0000, v101
	v_pk_mul_f32 v[216:217], v[130:131], v[216:217] op_sel_hi:[0,1]
	v_pk_fma_f32 v[216:217], v[8:9], v[216:217], v[136:137]
	v_pk_mul_f32 v[218:219], v[130:131], v[218:219] op_sel_hi:[0,1]
	v_pk_fma_f32 v[218:219], v[10:11], v[218:219], v[138:139]
	global_store_dwordx4 v[250:251], v[216:219], off offset:2048
	v_lshlrev_b32_e32 v136, 16, v102
	v_and_b32_e32 v137, 0xffff0000, v102
	v_lshlrev_b32_e32 v138, 16, v103
	v_and_b32_e32 v139, 0xffff0000, v103
	v_pk_mul_f32 v[220:221], v[130:131], v[220:221] op_sel_hi:[0,1]
	v_pk_fma_f32 v[220:221], v[12:13], v[220:221], v[136:137]
	v_pk_mul_f32 v[222:223], v[130:131], v[222:223] op_sel_hi:[0,1]
	v_pk_fma_f32 v[222:223], v[14:15], v[222:223], v[138:139]
	global_store_dwordx4 v[250:251], v[220:223], off offset:3072
	v_lshlrev_b32_e32 v136, 16, v104
	v_and_b32_e32 v137, 0xffff0000, v104
	v_lshlrev_b32_e32 v138, 16, v105
	v_and_b32_e32 v139, 0xffff0000, v105
	v_pk_mul_f32 v[224:225], v[130:131], v[224:225] op_sel_hi:[0,1]
	v_pk_fma_f32 v[224:225], v[16:17], v[224:225], v[136:137]
	v_pk_mul_f32 v[226:227], v[130:131], v[226:227] op_sel_hi:[0,1]
	v_pk_fma_f32 v[226:227], v[18:19], v[226:227], v[138:139]
	global_store_dwordx4 v[140:141], v[224:227], off offset:0
	v_lshlrev_b32_e32 v136, 16, v106
	v_and_b32_e32 v137, 0xffff0000, v106
	v_lshlrev_b32_e32 v138, 16, v107
	v_and_b32_e32 v139, 0xffff0000, v107
	v_pk_mul_f32 v[228:229], v[130:131], v[228:229] op_sel_hi:[0,1]
	v_pk_fma_f32 v[228:229], v[20:21], v[228:229], v[136:137]
	v_pk_mul_f32 v[230:231], v[130:131], v[230:231] op_sel_hi:[0,1]
	v_pk_fma_f32 v[230:231], v[22:23], v[230:231], v[138:139]
	global_store_dwordx4 v[140:141], v[228:231], off offset:1024
	v_lshlrev_b32_e32 v136, 16, v108
	v_and_b32_e32 v137, 0xffff0000, v108
	v_lshlrev_b32_e32 v138, 16, v109
	v_and_b32_e32 v139, 0xffff0000, v109
	v_pk_mul_f32 v[232:233], v[130:131], v[232:233] op_sel_hi:[0,1]
	v_pk_fma_f32 v[232:233], v[24:25], v[232:233], v[136:137]
	v_pk_mul_f32 v[234:235], v[130:131], v[234:235] op_sel_hi:[0,1]
	v_pk_fma_f32 v[234:235], v[26:27], v[234:235], v[138:139]
	global_store_dwordx4 v[140:141], v[232:235], off offset:2048
	v_lshlrev_b32_e32 v136, 16, v110
	v_and_b32_e32 v137, 0xffff0000, v110
	v_lshlrev_b32_e32 v138, 16, v111
	v_and_b32_e32 v139, 0xffff0000, v111
	v_pk_mul_f32 v[236:237], v[130:131], v[236:237] op_sel_hi:[0,1]
	v_pk_fma_f32 v[236:237], v[28:29], v[236:237], v[136:137]
	v_pk_mul_f32 v[238:239], v[130:131], v[238:239] op_sel_hi:[0,1]
	v_pk_fma_f32 v[238:239], v[30:31], v[238:239], v[138:139]
	global_store_dwordx4 v[140:141], v[236:239], off offset:3072
	v_lshl_add_u64 v[250:251], v[250:251], 0, s[12:13]
	s_waitcnt vmcnt(16)
	v_lshlrev_b32_e32 v208, 16, v160
	v_and_b32_e32 v209, 0xffff0000, v160
	v_lshlrev_b32_e32 v210, 16, v161
	v_and_b32_e32 v211, 0xffff0000, v161
	v_lshlrev_b32_e32 v212, 16, v162
	v_and_b32_e32 v213, 0xffff0000, v162
	v_lshlrev_b32_e32 v214, 16, v163
	v_and_b32_e32 v215, 0xffff0000, v163
	v_lshlrev_b32_e32 v216, 16, v164
	v_and_b32_e32 v217, 0xffff0000, v164
	v_lshlrev_b32_e32 v218, 16, v165
	v_and_b32_e32 v219, 0xffff0000, v165
	v_lshlrev_b32_e32 v220, 16, v166
	v_and_b32_e32 v221, 0xffff0000, v166
	v_lshlrev_b32_e32 v222, 16, v167
	v_and_b32_e32 v223, 0xffff0000, v167
	v_lshlrev_b32_e32 v224, 16, v168
	v_and_b32_e32 v225, 0xffff0000, v168
	v_lshlrev_b32_e32 v226, 16, v169
	v_and_b32_e32 v227, 0xffff0000, v169
	v_lshlrev_b32_e32 v228, 16, v170
	v_and_b32_e32 v229, 0xffff0000, v170
	v_lshlrev_b32_e32 v230, 16, v171
	v_and_b32_e32 v231, 0xffff0000, v171
	v_lshlrev_b32_e32 v232, 16, v172
	v_and_b32_e32 v233, 0xffff0000, v172
	v_lshlrev_b32_e32 v234, 16, v173
	v_and_b32_e32 v235, 0xffff0000, v173
	v_lshlrev_b32_e32 v236, 16, v174
	v_and_b32_e32 v237, 0xffff0000, v174
	v_lshlrev_b32_e32 v238, 16, v175
	v_and_b32_e32 v239, 0xffff0000, v175
	v_mul_f32_e32 v128, v208, v208
	v_fmac_f32_e32 v128, v209, v209
	v_mul_f32_e32 v129, v210, v210
	v_fmac_f32_e32 v129, v211, v211
	v_add_f32_e32 v128, v128, v129
	v_mul_f32_e32 v129, v212, v212
	v_fmac_f32_e32 v129, v213, v213
	v_mul_f32_e32 v132, v214, v214
	v_fmac_f32_e32 v132, v215, v215
	v_add_f32_e32 v129, v129, v132
	v_add_f32_e32 v128, v128, v129
	v_mul_f32_e32 v129, v216, v216
	v_fmac_f32_e32 v129, v217, v217
	v_mul_f32_e32 v132, v218, v218
	v_fmac_f32_e32 v132, v219, v219
	v_add_f32_e32 v129, v129, v132
	v_add_f32_e32 v128, v128, v129
	v_mul_f32_e32 v129, v220, v220
	v_fmac_f32_e32 v129, v221, v221
	v_mul_f32_e32 v132, v222, v222
	v_fmac_f32_e32 v132, v223, v223
	v_add_f32_e32 v129, v129, v132
	v_add_f32_e32 v128, v128, v129
	v_mul_f32_e32 v129, v224, v224
	v_fmac_f32_e32 v129, v225, v225
	v_mul_f32_e32 v132, v226, v226
	v_fmac_f32_e32 v132, v227, v227
	v_add_f32_e32 v129, v129, v132
	v_add_f32_e32 v128, v128, v129
	v_mul_f32_e32 v129, v228, v228
	v_fmac_f32_e32 v129, v229, v229
	v_mul_f32_e32 v132, v230, v230
	v_fmac_f32_e32 v132, v231, v231
	v_add_f32_e32 v129, v129, v132
	v_add_f32_e32 v128, v128, v129
	v_mul_f32_e32 v129, v232, v232
	v_fmac_f32_e32 v129, v233, v233
	v_mul_f32_e32 v132, v234, v234
	v_fmac_f32_e32 v132, v235, v235
	v_add_f32_e32 v129, v129, v132
	v_add_f32_e32 v128, v128, v129
	v_mul_f32_e32 v129, v236, v236
	v_fmac_f32_e32 v129, v237, v237
	v_mul_f32_e32 v132, v238, v238
	v_fmac_f32_e32 v132, v239, v239
	v_add_f32_e32 v129, v129, v132
	v_add_f32_e32 v128, v128, v129
	ds_bpermute_b32 v129, v244, v128
	s_waitcnt lgkmcnt(0)
	v_add_f32_e32 v128, v128, v129
	ds_bpermute_b32 v129, v245, v128
	s_waitcnt lgkmcnt(0)
	v_add_f32_e32 v128, v128, v129
	ds_bpermute_b32 v129, v246, v128
	s_waitcnt lgkmcnt(0)
	v_add_f32_e32 v128, v128, v129
	ds_bpermute_b32 v129, v247, v128
	s_waitcnt lgkmcnt(0)
	v_add_f32_e32 v128, v128, v129
	ds_bpermute_b32 v129, v248, v128
	s_waitcnt lgkmcnt(0)
	v_add_f32_e32 v128, v128, v129
	ds_bpermute_b32 v129, v249, v128
	s_waitcnt lgkmcnt(0)
	v_add_f32_e32 v128, v128, v129
	v_fmamk_f32 v128, v128, 0x3a000000, v255
	v_mul_f32_e32 v129, 0x4b800000, v128
	v_cmp_gt_f32_e32 vcc, s10, v128
	s_nop 1
	v_cndmask_b32_e32 v128, v128, v129, vcc
	v_rsq_f32_e32 v128, v128
	s_nop 0
	v_mul_f32_e32 v129, 0x45800000, v128
	v_cndmask_b32_e32 v130, v128, v129, vcc
	v_lshl_add_u64 v[140:141], v[250:251], 0, s[14:15]
	v_lshlrev_b32_e32 v136, 16, v144
	v_and_b32_e32 v137, 0xffff0000, v144
	v_lshlrev_b32_e32 v138, 16, v145
	v_and_b32_e32 v139, 0xffff0000, v145
	v_pk_mul_f32 v[208:209], v[130:131], v[208:209] op_sel_hi:[0,1]
	v_pk_fma_f32 v[208:209], v[0:1], v[208:209], v[136:137]
	v_pk_mul_f32 v[210:211], v[130:131], v[210:211] op_sel_hi:[0,1]
	v_pk_fma_f32 v[210:211], v[2:3], v[210:211], v[138:139]
	global_store_dwordx4 v[250:251], v[208:211], off offset:0
	v_lshlrev_b32_e32 v136, 16, v146
	v_and_b32_e32 v137, 0xffff0000, v146
	v_lshlrev_b32_e32 v138, 16, v147
	v_and_b32_e32 v139, 0xffff0000, v147
	v_pk_mul_f32 v[212:213], v[130:131], v[212:213] op_sel_hi:[0,1]
	v_pk_fma_f32 v[212:213], v[4:5], v[212:213], v[136:137]
	v_pk_mul_f32 v[214:215], v[130:131], v[214:215] op_sel_hi:[0,1]
	v_pk_fma_f32 v[214:215], v[6:7], v[214:215], v[138:139]
	global_store_dwordx4 v[250:251], v[212:215], off offset:1024
	v_lshlrev_b32_e32 v136, 16, v148
	v_and_b32_e32 v137, 0xffff0000, v148
	v_lshlrev_b32_e32 v138, 16, v149
	v_and_b32_e32 v139, 0xffff0000, v149
	v_pk_mul_f32 v[216:217], v[130:131], v[216:217] op_sel_hi:[0,1]
	v_pk_fma_f32 v[216:217], v[8:9], v[216:217], v[136:137]
	v_pk_mul_f32 v[218:219], v[130:131], v[218:219] op_sel_hi:[0,1]
	v_pk_fma_f32 v[218:219], v[10:11], v[218:219], v[138:139]
	global_store_dwordx4 v[250:251], v[216:219], off offset:2048
	v_lshlrev_b32_e32 v136, 16, v150
	v_and_b32_e32 v137, 0xffff0000, v150
	v_lshlrev_b32_e32 v138, 16, v151
	v_and_b32_e32 v139, 0xffff0000, v151
	v_pk_mul_f32 v[220:221], v[130:131], v[220:221] op_sel_hi:[0,1]
	v_pk_fma_f32 v[220:221], v[12:13], v[220:221], v[136:137]
	v_pk_mul_f32 v[222:223], v[130:131], v[222:223] op_sel_hi:[0,1]
	v_pk_fma_f32 v[222:223], v[14:15], v[222:223], v[138:139]
	global_store_dwordx4 v[250:251], v[220:223], off offset:3072
	v_lshlrev_b32_e32 v136, 16, v152
	v_and_b32_e32 v137, 0xffff0000, v152
	v_lshlrev_b32_e32 v138, 16, v153
	v_and_b32_e32 v139, 0xffff0000, v153
	v_pk_mul_f32 v[224:225], v[130:131], v[224:225] op_sel_hi:[0,1]
	v_pk_fma_f32 v[224:225], v[16:17], v[224:225], v[136:137]
	v_pk_mul_f32 v[226:227], v[130:131], v[226:227] op_sel_hi:[0,1]
	v_pk_fma_f32 v[226:227], v[18:19], v[226:227], v[138:139]
	global_store_dwordx4 v[140:141], v[224:227], off offset:0
	v_lshlrev_b32_e32 v136, 16, v154
	v_and_b32_e32 v137, 0xffff0000, v154
	v_lshlrev_b32_e32 v138, 16, v155
	v_and_b32_e32 v139, 0xffff0000, v155
	v_pk_mul_f32 v[228:229], v[130:131], v[228:229] op_sel_hi:[0,1]
	v_pk_fma_f32 v[228:229], v[20:21], v[228:229], v[136:137]
	v_pk_mul_f32 v[230:231], v[130:131], v[230:231] op_sel_hi:[0,1]
	v_pk_fma_f32 v[230:231], v[22:23], v[230:231], v[138:139]
	global_store_dwordx4 v[140:141], v[228:231], off offset:1024
	v_lshlrev_b32_e32 v136, 16, v156
	v_and_b32_e32 v137, 0xffff0000, v156
	v_lshlrev_b32_e32 v138, 16, v157
	v_and_b32_e32 v139, 0xffff0000, v157
	v_pk_mul_f32 v[232:233], v[130:131], v[232:233] op_sel_hi:[0,1]
	v_pk_fma_f32 v[232:233], v[24:25], v[232:233], v[136:137]
	v_pk_mul_f32 v[234:235], v[130:131], v[234:235] op_sel_hi:[0,1]
	v_pk_fma_f32 v[234:235], v[26:27], v[234:235], v[138:139]
	global_store_dwordx4 v[140:141], v[232:235], off offset:2048
	v_lshlrev_b32_e32 v136, 16, v158
	v_and_b32_e32 v137, 0xffff0000, v158
	v_lshlrev_b32_e32 v138, 16, v159
	v_and_b32_e32 v139, 0xffff0000, v159
	v_pk_mul_f32 v[236:237], v[130:131], v[236:237] op_sel_hi:[0,1]
	v_pk_fma_f32 v[236:237], v[28:29], v[236:237], v[136:137]
	v_pk_mul_f32 v[238:239], v[130:131], v[238:239] op_sel_hi:[0,1]
	v_pk_fma_f32 v[238:239], v[30:31], v[238:239], v[138:139]
	global_store_dwordx4 v[140:141], v[236:239], off offset:3072
	v_lshl_add_u64 v[250:251], v[250:251], 0, s[12:13]
	s_cmpk_gt_i32 s96, 0x1ff
	s_cbranch_scc1 .LBB0_1608
	s_waitcnt vmcnt(16)
	v_lshlrev_b32_e32 v208, 16, v192
	v_and_b32_e32 v209, 0xffff0000, v192
	v_lshlrev_b32_e32 v210, 16, v193
	v_and_b32_e32 v211, 0xffff0000, v193
	v_lshlrev_b32_e32 v212, 16, v194
	v_and_b32_e32 v213, 0xffff0000, v194
	v_lshlrev_b32_e32 v214, 16, v195
	v_and_b32_e32 v215, 0xffff0000, v195
	v_lshlrev_b32_e32 v216, 16, v196
	v_and_b32_e32 v217, 0xffff0000, v196
	v_lshlrev_b32_e32 v218, 16, v197
	v_and_b32_e32 v219, 0xffff0000, v197
	v_lshlrev_b32_e32 v220, 16, v198
	v_and_b32_e32 v221, 0xffff0000, v198
	v_lshlrev_b32_e32 v222, 16, v199
	v_and_b32_e32 v223, 0xffff0000, v199
	v_lshlrev_b32_e32 v224, 16, v200
	v_and_b32_e32 v225, 0xffff0000, v200
	v_lshlrev_b32_e32 v226, 16, v201
	v_and_b32_e32 v227, 0xffff0000, v201
	v_lshlrev_b32_e32 v228, 16, v202
	v_and_b32_e32 v229, 0xffff0000, v202
	v_lshlrev_b32_e32 v230, 16, v203
	v_and_b32_e32 v231, 0xffff0000, v203
	v_lshlrev_b32_e32 v232, 16, v204
	v_and_b32_e32 v233, 0xffff0000, v204
	v_lshlrev_b32_e32 v234, 16, v205
	v_and_b32_e32 v235, 0xffff0000, v205
	v_lshlrev_b32_e32 v236, 16, v206
	v_and_b32_e32 v237, 0xffff0000, v206
	v_lshlrev_b32_e32 v238, 16, v207
	v_and_b32_e32 v239, 0xffff0000, v207
	v_mul_f32_e32 v128, v208, v208
	v_fmac_f32_e32 v128, v209, v209
	v_mul_f32_e32 v129, v210, v210
	v_fmac_f32_e32 v129, v211, v211
	v_add_f32_e32 v128, v128, v129
	v_mul_f32_e32 v129, v212, v212
	v_fmac_f32_e32 v129, v213, v213
	v_mul_f32_e32 v132, v214, v214
	v_fmac_f32_e32 v132, v215, v215
	v_add_f32_e32 v129, v129, v132
	v_add_f32_e32 v128, v128, v129
	v_mul_f32_e32 v129, v216, v216
	v_fmac_f32_e32 v129, v217, v217
	v_mul_f32_e32 v132, v218, v218
	v_fmac_f32_e32 v132, v219, v219
	v_add_f32_e32 v129, v129, v132
	v_add_f32_e32 v128, v128, v129
	v_mul_f32_e32 v129, v220, v220
	v_fmac_f32_e32 v129, v221, v221
	v_mul_f32_e32 v132, v222, v222
	v_fmac_f32_e32 v132, v223, v223
	v_add_f32_e32 v129, v129, v132
	v_add_f32_e32 v128, v128, v129
	v_mul_f32_e32 v129, v224, v224
	v_fmac_f32_e32 v129, v225, v225
	v_mul_f32_e32 v132, v226, v226
	v_fmac_f32_e32 v132, v227, v227
	v_add_f32_e32 v129, v129, v132
	v_add_f32_e32 v128, v128, v129
	v_mul_f32_e32 v129, v228, v228
	v_fmac_f32_e32 v129, v229, v229
	v_mul_f32_e32 v132, v230, v230
	v_fmac_f32_e32 v132, v231, v231
	v_add_f32_e32 v129, v129, v132
	v_add_f32_e32 v128, v128, v129
	v_mul_f32_e32 v129, v232, v232
	v_fmac_f32_e32 v129, v233, v233
	v_mul_f32_e32 v132, v234, v234
	v_fmac_f32_e32 v132, v235, v235
	v_add_f32_e32 v129, v129, v132
	v_add_f32_e32 v128, v128, v129
	v_mul_f32_e32 v129, v236, v236
	v_fmac_f32_e32 v129, v237, v237
	v_mul_f32_e32 v132, v238, v238
	v_fmac_f32_e32 v132, v239, v239
	v_add_f32_e32 v129, v129, v132
	v_add_f32_e32 v128, v128, v129
	ds_bpermute_b32 v129, v244, v128
	s_waitcnt lgkmcnt(0)
	v_add_f32_e32 v128, v128, v129
	ds_bpermute_b32 v129, v245, v128
	s_waitcnt lgkmcnt(0)
	v_add_f32_e32 v128, v128, v129
	ds_bpermute_b32 v129, v246, v128
	s_waitcnt lgkmcnt(0)
	v_add_f32_e32 v128, v128, v129
	ds_bpermute_b32 v129, v247, v128
	s_waitcnt lgkmcnt(0)
	v_add_f32_e32 v128, v128, v129
	ds_bpermute_b32 v129, v248, v128
	s_waitcnt lgkmcnt(0)
	v_add_f32_e32 v128, v128, v129
	ds_bpermute_b32 v129, v249, v128
	s_waitcnt lgkmcnt(0)
	v_add_f32_e32 v128, v128, v129
	v_fmamk_f32 v128, v128, 0x3a000000, v255
	v_mul_f32_e32 v129, 0x4b800000, v128
	v_cmp_gt_f32_e32 vcc, s10, v128
	s_nop 1
	v_cndmask_b32_e32 v128, v128, v129, vcc
	v_rsq_f32_e32 v128, v128
	s_nop 0
	v_mul_f32_e32 v129, 0x45800000, v128
	v_cndmask_b32_e32 v130, v128, v129, vcc
	v_lshl_add_u64 v[140:141], v[250:251], 0, s[14:15]
	v_lshlrev_b32_e32 v136, 16, v176
	v_and_b32_e32 v137, 0xffff0000, v176
	v_lshlrev_b32_e32 v138, 16, v177
	v_and_b32_e32 v139, 0xffff0000, v177
	v_pk_mul_f32 v[208:209], v[130:131], v[208:209] op_sel_hi:[0,1]
	v_pk_fma_f32 v[208:209], v[0:1], v[208:209], v[136:137]
	v_pk_mul_f32 v[210:211], v[130:131], v[210:211] op_sel_hi:[0,1]
	v_pk_fma_f32 v[210:211], v[2:3], v[210:211], v[138:139]
	global_store_dwordx4 v[250:251], v[208:211], off offset:0
	v_lshlrev_b32_e32 v136, 16, v178
	v_and_b32_e32 v137, 0xffff0000, v178
	v_lshlrev_b32_e32 v138, 16, v179
	v_and_b32_e32 v139, 0xffff0000, v179
	v_pk_mul_f32 v[212:213], v[130:131], v[212:213] op_sel_hi:[0,1]
	v_pk_fma_f32 v[212:213], v[4:5], v[212:213], v[136:137]
	v_pk_mul_f32 v[214:215], v[130:131], v[214:215] op_sel_hi:[0,1]
	v_pk_fma_f32 v[214:215], v[6:7], v[214:215], v[138:139]
	global_store_dwordx4 v[250:251], v[212:215], off offset:1024
	v_lshlrev_b32_e32 v136, 16, v180
	v_and_b32_e32 v137, 0xffff0000, v180
	v_lshlrev_b32_e32 v138, 16, v181
	v_and_b32_e32 v139, 0xffff0000, v181
	v_pk_mul_f32 v[216:217], v[130:131], v[216:217] op_sel_hi:[0,1]
	v_pk_fma_f32 v[216:217], v[8:9], v[216:217], v[136:137]
	v_pk_mul_f32 v[218:219], v[130:131], v[218:219] op_sel_hi:[0,1]
	v_pk_fma_f32 v[218:219], v[10:11], v[218:219], v[138:139]
	global_store_dwordx4 v[250:251], v[216:219], off offset:2048
	v_lshlrev_b32_e32 v136, 16, v182
	v_and_b32_e32 v137, 0xffff0000, v182
	v_lshlrev_b32_e32 v138, 16, v183
	v_and_b32_e32 v139, 0xffff0000, v183
	v_pk_mul_f32 v[220:221], v[130:131], v[220:221] op_sel_hi:[0,1]
	v_pk_fma_f32 v[220:221], v[12:13], v[220:221], v[136:137]
	v_pk_mul_f32 v[222:223], v[130:131], v[222:223] op_sel_hi:[0,1]
	v_pk_fma_f32 v[222:223], v[14:15], v[222:223], v[138:139]
	global_store_dwordx4 v[250:251], v[220:223], off offset:3072
	v_lshlrev_b32_e32 v136, 16, v184
	v_and_b32_e32 v137, 0xffff0000, v184
	v_lshlrev_b32_e32 v138, 16, v185
	v_and_b32_e32 v139, 0xffff0000, v185
	v_pk_mul_f32 v[224:225], v[130:131], v[224:225] op_sel_hi:[0,1]
	v_pk_fma_f32 v[224:225], v[16:17], v[224:225], v[136:137]
	v_pk_mul_f32 v[226:227], v[130:131], v[226:227] op_sel_hi:[0,1]
	v_pk_fma_f32 v[226:227], v[18:19], v[226:227], v[138:139]
	global_store_dwordx4 v[140:141], v[224:227], off offset:0
	v_lshlrev_b32_e32 v136, 16, v186
	v_and_b32_e32 v137, 0xffff0000, v186
	v_lshlrev_b32_e32 v138, 16, v187
	v_and_b32_e32 v139, 0xffff0000, v187
	v_pk_mul_f32 v[228:229], v[130:131], v[228:229] op_sel_hi:[0,1]
	v_pk_fma_f32 v[228:229], v[20:21], v[228:229], v[136:137]
	v_pk_mul_f32 v[230:231], v[130:131], v[230:231] op_sel_hi:[0,1]
	v_pk_fma_f32 v[230:231], v[22:23], v[230:231], v[138:139]
	global_store_dwordx4 v[140:141], v[228:231], off offset:1024
	v_lshlrev_b32_e32 v136, 16, v188
	v_and_b32_e32 v137, 0xffff0000, v188
	v_lshlrev_b32_e32 v138, 16, v189
	v_and_b32_e32 v139, 0xffff0000, v189
	v_pk_mul_f32 v[232:233], v[130:131], v[232:233] op_sel_hi:[0,1]
	v_pk_fma_f32 v[232:233], v[24:25], v[232:233], v[136:137]
	v_pk_mul_f32 v[234:235], v[130:131], v[234:235] op_sel_hi:[0,1]
	v_pk_fma_f32 v[234:235], v[26:27], v[234:235], v[138:139]
	global_store_dwordx4 v[140:141], v[232:235], off offset:2048
	v_lshlrev_b32_e32 v136, 16, v190
	v_and_b32_e32 v137, 0xffff0000, v190
	v_lshlrev_b32_e32 v138, 16, v191
	v_and_b32_e32 v139, 0xffff0000, v191
	v_pk_mul_f32 v[236:237], v[130:131], v[236:237] op_sel_hi:[0,1]
	v_pk_fma_f32 v[236:237], v[28:29], v[236:237], v[136:137]
	v_pk_mul_f32 v[238:239], v[130:131], v[238:239] op_sel_hi:[0,1]
	v_pk_fma_f32 v[238:239], v[30:31], v[238:239], v[138:139]
	global_store_dwordx4 v[140:141], v[236:239], off offset:3072
	v_lshl_add_u64 v[250:251], v[250:251], 0, s[12:13]
